# no DQ copy (q read in place, scale folded) + sb units prefetch the next unit's q and first K tile
# baseline (speedup 1.0000x reference)
.LBB0_352:
	s_or_b64 exec, exec, s[0:1]
	v_readfirstlane_b32 s2, v0
	s_cmpk_gt_i32 s2, 0x1ff
	s_cbranch_scc1 .LBB0_361
	s_mov_b32 s13, 0
	s_add_u32 s10, s54, 0x2a080000
	s_addc_u32 s11, s55, 0
	s_add_u32 s14, s54, 0x2c080000
	s_addc_u32 s15, s55, 0
	s_add_u32 s16, s54, 0x2b080000
	s_addc_u32 s17, s55, 0

.LBB0_358:
	s_or_b64 exec, exec, s[0:1]
	s_lshr_b32 s3, s2, 6
	s_and_b32 s0, s2, 63
	s_sub_i32 s12, 63, s0
	v_readlane_b32 s0, v253, 31
	v_and_b32_e32 v152, 31, v186
	v_bfe_u32 v153, v186, 5, 1
	s_lshl_b32 s1, s0, 2
	s_add_i32 s1, s1, s3
	s_lshl_b32 s1, s1, 18
	s_add_u32 s40, s16, s1
	s_addc_u32 s41, s17, 0
	s_add_u32 s42, s14, s1
	s_addc_u32 s43, s15, 0
	s_lshl_b32 s1, s0, 10
	s_lshl_b32 s4, s12, 5
	s_add_i32 s1, s1, s4
	v_add_u32_e32 v154, s1, v152
	v_mul_u32_u24_e32 v155, s66, v154
	v_lshl_add_u32 v155, v153, 4, v155
	s_lshl_b32 s1, s3, 7
	s_add_u32 s4, s54, s1
	s_addc_u32 s5, s55, 0
	s_add_u32 s4, s4, 0xa001e30
	s_addc_u32 s5, s5, 0
	s_cmp_eq_u32 s13, 1
	s_cbranch_scc1 .Lsb_haveq
	global_load_dwordx4 v[48:51], v155, s[4:5]
	global_load_dwordx4 v[52:55], v155, s[4:5] offset:32
	global_load_dwordx4 v[56:59], v155, s[4:5] offset:64
	global_load_dwordx4 v[60:63], v155, s[4:5] offset:96
.Lsb_haveq:
	v_and_b32_e32 v200, 63, v186
	v_lshlrev_b32_e32 v200, 4, v200
	v_lshlrev_b32_e32 v201, 5, v152
	v_lshl_add_u32 v201, v153, 4, v201
	s_lshl_b32 s1, s12, 12
	s_add_u32 s4, s40, s1
	s_addc_u32 s5, s41, 0
	s_cmp_eq_u32 s13, 1
	s_cbranch_scc1 .Lsb_havek
	global_load_dwordx4 v[66:69], v200, s[4:5]
	global_load_dwordx4 v[70:73], v200, s[4:5] offset:1024
	global_load_dwordx4 v[74:77], v200, s[4:5] offset:2048
	global_load_dwordx4 v[78:81], v200, s[4:5] offset:3072
	s_branch .Lsb_ownld
.Lsb_havek:
	v_mov_b32_e32 v48, v202
	v_mov_b32_e32 v49, v203
	v_mov_b32_e32 v50, v204
	v_mov_b32_e32 v51, v205
	v_mov_b32_e32 v52, v206
	v_mov_b32_e32 v53, v207
	v_mov_b32_e32 v54, v208
	v_mov_b32_e32 v55, v209
	v_mov_b32_e32 v56, v210
	v_mov_b32_e32 v57, v211
	v_mov_b32_e32 v58, v212
	v_mov_b32_e32 v59, v213
	v_mov_b32_e32 v60, v214
	v_mov_b32_e32 v61, v215
	v_mov_b32_e32 v62, v216
	v_mov_b32_e32 v63, v217
	v_mov_b32_e32 v66, v218
	v_mov_b32_e32 v67, v219
	v_mov_b32_e32 v68, v220
	v_mov_b32_e32 v69, v221
	v_mov_b32_e32 v70, v222
	v_mov_b32_e32 v71, v223
	v_mov_b32_e32 v72, v224
	v_mov_b32_e32 v73, v225
	v_mov_b32_e32 v74, v226
	v_mov_b32_e32 v75, v227
	v_mov_b32_e32 v76, v228
	v_mov_b32_e32 v77, v229
	v_mov_b32_e32 v78, v230
	v_mov_b32_e32 v79, v231
	v_mov_b32_e32 v80, v232
	v_mov_b32_e32 v81, v233
.Lsb_ownld:
	v_xor_b32_e32 v114, 32, v190
	v_lshlrev_b32_e32 v114, 2, v114
	v_lshlrev_b32_e32 v115, 2, v153
	v_sub_u32_e32 v115, v152, v115
	v_sub_u32_e32 v116, 1, v153
	v_sub_u32_e32 v116, 0, v116
	v_lshlrev_b32_e32 v156, 13, v154
	v_lshl_add_u32 v156, v153, 4, v156
	s_lshl_b32 s1, s3, 8
	s_add_i32 s1, s1, 0x1800
	v_add_u32_e32 v156, s1, v156
	s_add_u32 s4, s54, 0x20000000
	s_addc_u32 s5, s55, 0
	v_mov_b32_e32 v161, s5
	v_add_co_u32_e32 v160, vcc, s4, v156
	s_nop 1
	v_addc_co_u32_e32 v161, vcc, 0, v161, vcc
	v_mov_b32_e32 v127, 0
	v_mov_b32_e32 v0, 0
	v_mov_b32_e32 v1, 0
	v_mov_b32_e32 v2, 0
	v_mov_b32_e32 v3, 0
	v_mov_b32_e32 v4, 0
	v_mov_b32_e32 v5, 0
	v_mov_b32_e32 v6, 0
	v_mov_b32_e32 v7, 0
	v_mov_b32_e32 v8, 0
	v_mov_b32_e32 v9, 0
	v_mov_b32_e32 v10, 0
	v_mov_b32_e32 v11, 0
	v_mov_b32_e32 v12, 0
	v_mov_b32_e32 v13, 0
	v_mov_b32_e32 v14, 0
	v_mov_b32_e32 v15, 0
	v_mov_b32_e32 v16, 0
	v_mov_b32_e32 v17, 0
	v_mov_b32_e32 v18, 0
	v_mov_b32_e32 v19, 0
	v_mov_b32_e32 v20, 0
	v_mov_b32_e32 v21, 0
	v_mov_b32_e32 v22, 0
	v_mov_b32_e32 v23, 0
	v_mov_b32_e32 v24, 0
	v_mov_b32_e32 v25, 0
	v_mov_b32_e32 v26, 0
	v_mov_b32_e32 v27, 0
	v_mov_b32_e32 v28, 0
	v_mov_b32_e32 v29, 0
	v_mov_b32_e32 v30, 0
	v_mov_b32_e32 v31, 0
	s_sub_i32 s0, s12, 1
	s_max_i32 s0, s0, 0
	s_lshl_b32 s0, s0, 12
	s_add_u32 s2, s40, s0
	s_addc_u32 s3, s41, 0
	s_lshl_b32 s0, s12, 12
	s_add_u32 s18, s42, s0
	s_addc_u32 s19, s43, 0
	s_waitcnt vmcnt(0)
	global_load_dwordx4 v[82:85], v200, s[2:3]
	global_load_dwordx4 v[86:89], v200, s[2:3] offset:1024
	global_load_dwordx4 v[90:93], v200, s[2:3] offset:2048
	global_load_dwordx4 v[94:97], v200, s[2:3] offset:3072
	global_load_dwordx4 v[98:101], v201, s[18:19]
	global_load_dwordx4 v[102:105], v201, s[18:19] offset:1024
	global_load_dwordx4 v[106:109], v201, s[18:19] offset:2048
	global_load_dwordx4 v[110:113], v201, s[18:19] offset:3072
	v_readfirstlane_b32 s20, v118
	s_mov_b32 s13, 0
	s_cmpk_gt_i32 s20, 0x1ff
	s_cbranch_scc1 .Lsb_nopf
	s_lshr_b32 s21, s20, 6
	s_and_b32 s22, s20, 63
	s_sub_i32 s22, 63, s22
	v_readlane_b32 s23, v253, 31
	s_lshl_b32 s24, s23, 2
	s_add_i32 s24, s24, s21
	s_lshl_b32 s24, s24, 18
	s_add_u32 s26, s16, s24
	s_addc_u32 s27, s17, 0
	s_lshl_b32 s24, s22, 12
	s_add_u32 s26, s26, s24
	s_addc_u32 s27, s27, 0
	global_load_dwordx4 v[218:221], v200, s[26:27]
	global_load_dwordx4 v[222:225], v200, s[26:27] offset:1024
	global_load_dwordx4 v[226:229], v200, s[26:27] offset:2048
	global_load_dwordx4 v[230:233], v200, s[26:27] offset:3072
	s_lshl_b32 s24, s23, 10
	s_lshl_b32 s25, s22, 5
	s_add_i32 s24, s24, s25
	v_and_b32_e32 v234, 31, v186
	v_bfe_u32 v235, v186, 5, 1
	v_add_u32_e32 v234, s24, v234
	v_mul_u32_u24_e32 v234, s66, v234
	v_lshl_add_u32 v234, v235, 4, v234
	s_lshl_b32 s24, s21, 7
	s_add_u32 s26, s54, s24
	s_addc_u32 s27, s55, 0
	s_add_u32 s26, s26, 0xa001e30
	s_addc_u32 s27, s27, 0
	global_load_dwordx4 v[202:205], v234, s[26:27]
	global_load_dwordx4 v[206:209], v234, s[26:27] offset:32
	global_load_dwordx4 v[210:213], v234, s[26:27] offset:64
	global_load_dwordx4 v[214:217], v234, s[26:27] offset:96
	s_mov_b32 s13, 1
.Lsb_nopf:
	v_mfma_f32_32x32x16_bf16 v[32:47], v[66:69], v[48:51], 0
	v_mfma_f32_32x32x16_bf16 v[32:47], v[70:73], v[52:55], v[32:47]
	v_mfma_f32_32x32x16_bf16 v[32:47], v[74:77], v[56:59], v[32:47]
	v_mfma_f32_32x32x16_bf16 v[32:47], v[78:81], v[60:63], v[32:47]
	s_nop 11
	v_mul_f32_e32 v44, 0x3e38aa3b, v44
	v_mul_f32_e32 v45, 0x3e38aa3b, v45
	v_mul_f32_e32 v46, 0x3e38aa3b, v46
	v_mul_f32_e32 v47, 0x3e38aa3b, v47
	v_exp_f32_e64 v152, -|v44|
	v_exp_f32_e64 v153, -|v45|
	v_exp_f32_e64 v154, -|v46|
	v_exp_f32_e64 v155, -|v47|
	v_max_f32_e32 v140, 0, v44
	v_max_f32_e32 v141, 0, v45
	v_max_f32_e32 v142, 0, v46
	v_max_f32_e32 v143, 0, v47
	v_add_f32_e32 v152, 1.0, v152
	v_add_f32_e32 v153, 1.0, v153
	v_add_f32_e32 v154, 1.0, v154
	v_add_f32_e32 v155, 1.0, v155
	v_log_f32_e32 v152, v152
	v_log_f32_e32 v153, v153
	v_log_f32_e32 v154, v154
	v_log_f32_e32 v155, v155
	s_nop 0
	v_add_f32_e32 v140, v140, v152
	v_add_f32_e32 v141, v141, v153
	v_add_f32_e32 v142, v142, v154
	v_add_f32_e32 v143, v143, v155
	v_cmp_lt_i32_e64 s[0:1], 24, v115
	v_cmp_lt_i32_e64 s[2:3], 25, v115
	v_cmp_lt_i32_e64 s[4:5], 26, v115
	v_cmp_lt_i32_e64 s[6:7], 27, v115
	s_nop 1
	v_cndmask_b32_e64 v140, 0, v140, s[0:1]
	v_cndmask_b32_e64 v141, 0, v141, s[2:3]
	v_cndmask_b32_e64 v142, 0, v142, s[4:5]
	v_cndmask_b32_e64 v143, 0, v143, s[6:7]
	v_add_f32_e32 v152, v140, v141
	v_add_f32_e32 v153, v142, v143
	v_add_f32_e32 v122, v152, v153
	ds_bpermute_b32 v126, v114, v122
	v_mul_f32_e32 v40, 0x3e38aa3b, v40
	v_mul_f32_e32 v41, 0x3e38aa3b, v41
	v_mul_f32_e32 v42, 0x3e38aa3b, v42
	v_mul_f32_e32 v43, 0x3e38aa3b, v43
	v_exp_f32_e64 v152, -|v40|
	v_exp_f32_e64 v153, -|v41|
	v_exp_f32_e64 v154, -|v42|
	v_exp_f32_e64 v155, -|v43|
	v_max_f32_e32 v136, 0, v40
	v_max_f32_e32 v137, 0, v41
	v_max_f32_e32 v138, 0, v42
	v_max_f32_e32 v139, 0, v43
	v_add_f32_e32 v152, 1.0, v152
	v_add_f32_e32 v153, 1.0, v153
	v_add_f32_e32 v154, 1.0, v154
	v_add_f32_e32 v155, 1.0, v155
	v_log_f32_e32 v152, v152
	v_log_f32_e32 v153, v153
	v_log_f32_e32 v154, v154
	v_log_f32_e32 v155, v155
	s_nop 0
	v_add_f32_e32 v136, v136, v152
	v_add_f32_e32 v137, v137, v153
	v_add_f32_e32 v138, v138, v154
	v_add_f32_e32 v139, v139, v155
	v_cmp_lt_i32_e64 s[0:1], 16, v115
	v_cmp_lt_i32_e64 s[2:3], 17, v115
	v_cmp_lt_i32_e64 s[4:5], 18, v115
	v_cmp_lt_i32_e64 s[6:7], 19, v115
	s_nop 1
	v_cndmask_b32_e64 v136, 0, v136, s[0:1]
	v_cndmask_b32_e64 v137, 0, v137, s[2:3]
	v_cndmask_b32_e64 v138, 0, v138, s[4:5]
	v_cndmask_b32_e64 v139, 0, v139, s[6:7]
	v_add_f32_e32 v152, v136, v137
	v_add_f32_e32 v153, v138, v139
	v_add_f32_e32 v121, v152, v153
	ds_bpermute_b32 v125, v114, v121
	v_mul_f32_e32 v36, 0x3e38aa3b, v36
	v_mul_f32_e32 v37, 0x3e38aa3b, v37
	v_mul_f32_e32 v38, 0x3e38aa3b, v38
	v_mul_f32_e32 v39, 0x3e38aa3b, v39
	v_exp_f32_e64 v152, -|v36|
	v_exp_f32_e64 v153, -|v37|
	v_exp_f32_e64 v154, -|v38|
	v_exp_f32_e64 v155, -|v39|
	v_max_f32_e32 v132, 0, v36
	v_max_f32_e32 v133, 0, v37
	v_max_f32_e32 v134, 0, v38
	v_max_f32_e32 v135, 0, v39
	v_add_f32_e32 v152, 1.0, v152
	v_add_f32_e32 v153, 1.0, v153
	v_add_f32_e32 v154, 1.0, v154
	v_add_f32_e32 v155, 1.0, v155
	v_log_f32_e32 v152, v152
	v_log_f32_e32 v153, v153
	v_log_f32_e32 v154, v154
	v_log_f32_e32 v155, v155
	s_nop 0
	v_add_f32_e32 v132, v132, v152
	v_add_f32_e32 v133, v133, v153
	v_add_f32_e32 v134, v134, v154
	v_add_f32_e32 v135, v135, v155
	v_cmp_lt_i32_e64 s[0:1], 8, v115
	v_cmp_lt_i32_e64 s[2:3], 9, v115
	v_cmp_lt_i32_e64 s[4:5], 10, v115
	v_cmp_lt_i32_e64 s[6:7], 11, v115
	s_nop 1
	v_cndmask_b32_e64 v132, 0, v132, s[0:1]
	v_cndmask_b32_e64 v133, 0, v133, s[2:3]
	v_cndmask_b32_e64 v134, 0, v134, s[4:5]
	v_cndmask_b32_e64 v135, 0, v135, s[6:7]
	v_add_f32_e32 v152, v132, v133
	v_add_f32_e32 v153, v134, v135
	v_add_f32_e32 v120, v152, v153
	ds_bpermute_b32 v124, v114, v120
	v_mul_f32_e32 v32, 0x3e38aa3b, v32
	v_mul_f32_e32 v33, 0x3e38aa3b, v33
	v_mul_f32_e32 v34, 0x3e38aa3b, v34
	v_mul_f32_e32 v35, 0x3e38aa3b, v35
	v_exp_f32_e64 v152, -|v32|
	v_exp_f32_e64 v153, -|v33|
	v_exp_f32_e64 v154, -|v34|
	v_exp_f32_e64 v155, -|v35|
	v_max_f32_e32 v128, 0, v32
	v_max_f32_e32 v129, 0, v33
	v_max_f32_e32 v130, 0, v34
	v_max_f32_e32 v131, 0, v35
	v_add_f32_e32 v152, 1.0, v152
	v_add_f32_e32 v153, 1.0, v153
	v_add_f32_e32 v154, 1.0, v154
	v_add_f32_e32 v155, 1.0, v155
	v_log_f32_e32 v152, v152
	v_log_f32_e32 v153, v153
	v_log_f32_e32 v154, v154
	v_log_f32_e32 v155, v155
	s_nop 0
	v_add_f32_e32 v128, v128, v152
	v_add_f32_e32 v129, v129, v153
	v_add_f32_e32 v130, v130, v154
	v_add_f32_e32 v131, v131, v155
	v_cmp_lt_i32_e64 s[0:1], 0, v115
	v_cmp_lt_i32_e64 s[2:3], 1, v115
	v_cmp_lt_i32_e64 s[4:5], 2, v115
	v_cmp_lt_i32_e64 s[6:7], 3, v115
	s_nop 1
	v_cndmask_b32_e64 v128, 0, v128, s[0:1]
	v_cndmask_b32_e64 v129, 0, v129, s[2:3]
	v_cndmask_b32_e64 v130, 0, v130, s[4:5]
	v_cndmask_b32_e64 v131, 0, v131, s[6:7]
	v_add_f32_e32 v152, v128, v129
	v_add_f32_e32 v153, v130, v131
	v_add_f32_e32 v119, v152, v153
	ds_bpermute_b32 v123, v114, v119
	s_waitcnt lgkmcnt(3)
	v_and_b32_e32 v152, v116, v126
	v_add_f32_e32 v153, v122, v126
	v_sub_f32_e32 v199, v127, v152
	v_sub_f32_e32 v127, v127, v153
	v_sub_f32_e32 v159, v199, v143
	v_sub_f32_e32 v158, v159, v142
	v_sub_f32_e32 v157, v158, v141
	v_sub_f32_e32 v156, v157, v140
	v_cmp_lt_i32_e64 s[0:1], 24, v115
	v_cmp_lt_i32_e64 s[2:3], 25, v115
	v_cmp_lt_i32_e64 s[4:5], 26, v115
	v_cmp_lt_i32_e64 s[6:7], 27, v115
	v_add_f32_e32 v44, v44, v156
	v_add_f32_e32 v45, v45, v157
	v_add_f32_e32 v46, v46, v158
	v_add_f32_e32 v47, v47, v159
	v_exp_f32_e32 v44, v44
	v_exp_f32_e32 v45, v45
	v_exp_f32_e32 v46, v46
	v_exp_f32_e32 v47, v47
	s_nop 0
	v_cndmask_b32_e64 v44, 0, v44, s[0:1]
	v_cndmask_b32_e64 v45, 0, v45, s[2:3]
	v_cndmask_b32_e64 v46, 0, v46, s[4:5]
	v_cndmask_b32_e64 v47, 0, v47, s[6:7]
	s_waitcnt lgkmcnt(2)
	v_and_b32_e32 v152, v116, v125
	v_add_f32_e32 v153, v121, v125
	v_sub_f32_e32 v199, v127, v152
	v_sub_f32_e32 v127, v127, v153
	v_sub_f32_e32 v159, v199, v139
	v_sub_f32_e32 v158, v159, v138
	v_sub_f32_e32 v157, v158, v137
	v_sub_f32_e32 v156, v157, v136
	v_cmp_lt_i32_e64 s[0:1], 16, v115
	v_cmp_lt_i32_e64 s[2:3], 17, v115
	v_cmp_lt_i32_e64 s[4:5], 18, v115
	v_cmp_lt_i32_e64 s[6:7], 19, v115
	v_add_f32_e32 v40, v40, v156
	v_add_f32_e32 v41, v41, v157
	v_add_f32_e32 v42, v42, v158
	v_add_f32_e32 v43, v43, v159
	v_exp_f32_e32 v40, v40
	v_exp_f32_e32 v41, v41
	v_exp_f32_e32 v42, v42
	v_exp_f32_e32 v43, v43
	s_nop 0
	v_cndmask_b32_e64 v40, 0, v40, s[0:1]
	v_cndmask_b32_e64 v41, 0, v41, s[2:3]
	v_cndmask_b32_e64 v42, 0, v42, s[4:5]
	v_cndmask_b32_e64 v43, 0, v43, s[6:7]
	s_waitcnt lgkmcnt(1)
	v_and_b32_e32 v152, v116, v124
	v_add_f32_e32 v153, v120, v124
	v_sub_f32_e32 v199, v127, v152
	v_sub_f32_e32 v127, v127, v153
	v_sub_f32_e32 v159, v199, v135
	v_sub_f32_e32 v158, v159, v134
	v_sub_f32_e32 v157, v158, v133
	v_sub_f32_e32 v156, v157, v132
	v_cmp_lt_i32_e64 s[0:1], 8, v115
	v_cmp_lt_i32_e64 s[2:3], 9, v115
	v_cmp_lt_i32_e64 s[4:5], 10, v115
	v_cmp_lt_i32_e64 s[6:7], 11, v115
	v_add_f32_e32 v36, v36, v156
	v_add_f32_e32 v37, v37, v157
	v_add_f32_e32 v38, v38, v158
	v_add_f32_e32 v39, v39, v159
	v_exp_f32_e32 v36, v36
	v_exp_f32_e32 v37, v37
	v_exp_f32_e32 v38, v38
	v_exp_f32_e32 v39, v39
	s_nop 0
	v_cndmask_b32_e64 v36, 0, v36, s[0:1]
	v_cndmask_b32_e64 v37, 0, v37, s[2:3]
	v_cndmask_b32_e64 v38, 0, v38, s[4:5]
	v_cndmask_b32_e64 v39, 0, v39, s[6:7]
	s_waitcnt lgkmcnt(0)
	v_and_b32_e32 v152, v116, v123
	v_add_f32_e32 v153, v119, v123
	v_sub_f32_e32 v199, v127, v152
	v_sub_f32_e32 v127, v127, v153
	v_sub_f32_e32 v159, v199, v131
	v_sub_f32_e32 v158, v159, v130
	v_sub_f32_e32 v157, v158, v129
	v_sub_f32_e32 v156, v157, v128
	v_cmp_lt_i32_e64 s[0:1], 0, v115
	v_cmp_lt_i32_e64 s[2:3], 1, v115
	v_cmp_lt_i32_e64 s[4:5], 2, v115
	v_cmp_lt_i32_e64 s[6:7], 3, v115
	v_add_f32_e32 v32, v32, v156
	v_add_f32_e32 v33, v33, v157
	v_add_f32_e32 v34, v34, v158
	v_add_f32_e32 v35, v35, v159
	v_exp_f32_e32 v32, v32
	v_exp_f32_e32 v33, v33
	v_exp_f32_e32 v34, v34
	v_exp_f32_e32 v35, v35
	s_nop 0
	v_cndmask_b32_e64 v32, 0, v32, s[0:1]
	v_cndmask_b32_e64 v33, 0, v33, s[2:3]
	v_cndmask_b32_e64 v34, 0, v34, s[4:5]
	v_cndmask_b32_e64 v35, 0, v35, s[6:7]
	v_cvt_pk_bf16_f32 v144, v32, v33
	v_cvt_pk_bf16_f32 v145, v34, v35
	v_cvt_pk_bf16_f32 v146, v36, v37
	v_cvt_pk_bf16_f32 v147, v38, v39
	v_cvt_pk_bf16_f32 v148, v40, v41
	v_cvt_pk_bf16_f32 v149, v42, v43
	v_cvt_pk_bf16_f32 v150, v44, v45
	v_cvt_pk_bf16_f32 v151, v46, v47
	v_cmp_gt_f32_e32 vcc, 0xc3177ba5, v127
	s_waitcnt vmcnt(0)
	v_mfma_f32_32x32x16_bf16 v[16:31], v[98:101], v[144:147], v[16:31]
	v_mfma_f32_32x32x16_bf16 v[0:15], v[102:105], v[144:147], v[0:15]
	v_mfma_f32_32x32x16_bf16 v[16:31], v[106:109], v[148:151], v[16:31]
	v_mfma_f32_32x32x16_bf16 v[0:15], v[110:113], v[148:151], v[0:15]
	s_cmp_eq_u64 vcc, exec
	s_cselect_b32 s0, 1, 0
	s_cmp_eq_u32 s12, 0
	s_cselect_b32 s1, 1, 0
	s_or_b32 s0, s0, s1
	s_sub_i32 s12, s12, 1
	s_cmp_lg_u32 s0, 0
	s_cbranch_scc1 .Lsb_done
